# GEMM K-loop MFMA hand-off between the two half-workgroups: s_setprio raised before the barrier, lowered after it, mid-block toggles and redundant lgkmcnt(0) removed from the hand-off path
# speedup vs baseline: 1.0087x; 1.0045x over previous
; #define S_STAGE(bufoff, gbase, voff) do { _Pragma("unroll") for (int _i = 0; _i < 2; ++_i) \
;     __builtin_amdgcn_global_load_lds((const unsigned*)((gbase) + (voff)[_i]), (LAS unsigned*)(lds + (bufoff) + ldsw + _i * 8192), 16, 0, 0); } while (0)
; #define S_LDA(dst, b, h) do { _Pragma("unroll") for (int m = 0; m < 4; ++m) _Pragma("unroll") for (int k = 0; k < 2; ++k) dst[m][k] = *(const LAS bf16x8*)(lds + S_SA(b, h) + aoff + m * 2048 + k * 1024); } while (0)
; #define S_LDB(dst, b, h) do { _Pragma("unroll") for (int n = 0; n < 2; ++n) _Pragma("unroll") for (int k = 0; k < 2; ++k) dst[n][k] = *(const LAS bf16x8*)(lds + S_SB(b, h) + boff + n * 2048 + k * 1024); } while (0)
; #define S_MMA(ai, bj, At_, Bt_) do { __builtin_amdgcn_s_setprio(1); _Pragma("unroll") for (int m = 0; m < 4; ++m) _Pragma("unroll") for (int n = 0; n < 2; ++n) _Pragma("unroll") for (int k = 0; k < 2; ++k) \
;     acc[ai][bj][m][n] = __builtin_amdgcn_mfma_f32_16x16x32_bf16(Bt_[n][k], At_[m][k], acc[ai][bj][m][n], 0, 0, 0); __builtin_amdgcn_s_setprio(0); } while (0)
; #define S_WAIT_V(n) asm volatile("s_waitcnt vmcnt(" #n ")" ::: "memory")
; #define S_WAIT_L(n) asm volatile("s_waitcnt lgkmcnt(" #n ")" ::: "memory")
; #define S_BAR __builtin_amdgcn_s_barrier()
; #define S_SCHED __builtin_amdgcn_sched_barrier(0)
; DI void gemm_phase(LAS unsigned char* lds, const GemmDesc& d, float* __restrict__ X) {
;     ...
;     for (int t = 0; t < nt; t += 2) {
;       const bool last = (t == nt - 2);
;       const char* a1 = cA + (size_t)(t + 1) * kstepA;
;       const char* a2 = last ? nA : cA + (size_t)(t + 2) * kstepA; const char* b2 = last ? nB : cB + (size_t)(t + 2) * kstepB;
;       const char* a3 = a2 + kstepA; const char* b3 = b2 + kstepB;
;       S_LDB(B0, 0, 0); S_LDB(B1, 0, 1); S_SCHED; S_LDA(At, 0, 0); S_STAGE(S_SA(1, 1), a1 + hstepA, voffA);
;       S_WAIT_V(8); S_WAIT_L(0); S_BAR; S_MMA(0, 0, At, B0); S_MMA(0, 1, At, B1); S_BAR; S_SCHED;
;       S_LDA(At, 0, 1); S_STAGE(S_SB(0, 0), b2, voffB); S_STAGE(S_SB(0, 1), b2 + hstepB, voffB); S_STAGE(S_SA(0, 0), a2, voffA);
;       S_WAIT_V(8); S_WAIT_L(0); S_BAR; S_MMA(1, 0, At, B0); S_MMA(1, 1, At, B1); S_BAR; S_SCHED;
.LBB0_346:
	s_add_u32 s14, s90, 1
	s_addc_u32 s15, s91, 0
	s_add_u32 vcc_lo, s90, 2
	s_addc_u32 vcc_hi, s91, 0
	s_lshl_b64 s[78:79], vcc, s8
	s_add_u32 s56, s88, s78
	s_addc_u32 s57, s89, s79
	s_cmp_eq_u32 s9, s90
	s_cselect_b32 s78, s12, s56
	s_cselect_b32 s79, s13, s57
	s_cselect_b32 s56, s86, s64
	s_cselect_b32 s57, s87, s69
	s_add_u32 s90, s78, s0
	s_addc_u32 s91, s79, 0
	s_add_i32 s93, 0, 0x10000
	v_add_u32_e32 v0, s93, v174
	s_add_i32 s6, 0, 0x14000
	ds_read_b128 v[130:133], v0
	ds_read_b128 v[134:137], v0 offset:1024
	ds_read_b128 v[138:141], v0 offset:2048
	ds_read_b128 v[142:145], v0 offset:3072
	v_add_u32_e32 v0, s6, v174
	ds_read_b128 v[158:161], v0
	ds_read_b128 v[162:165], v0 offset:1024
	ds_read_b128 v[166:169], v0 offset:2048
	ds_read_b128 v[170:173], v0 offset:3072
	s_lshl_b64 s[14:15], s[14:15], s8
	s_add_u32 s14, s20, s14
	s_addc_u32 s15, s21, s15
	v_lshl_add_u64 v[192:193], s[14:15], 0, v[148:149]
	s_add_i32 m0, s55, 0xc000
	ds_read_b128 v[180:183], v147
	ds_read_b128 v[184:187], v147 offset:1024
	ds_read_b128 v[188:191], v147 offset:2048
	ds_read_b128 v[196:199], v147 offset:3072
	ds_read_b128 v[200:203], v147 offset:4096
	ds_read_b128 v[216:219], v147 offset:5120
	ds_read_b128 v[222:225], v147 offset:6144
	ds_read_b128 v[226:229], v147 offset:7168
	global_load_lds_dwordx4 v[192:193], off
	v_lshl_add_u64 v[192:193], s[14:15], 0, v[152:153]
	s_add_i32 m0, s55, 0xe000
	s_nop 0
	global_load_lds_dwordx4 v[192:193], off
	s_waitcnt vmcnt(8)
	s_waitcnt lgkmcnt(0)
	s_setprio 1
	s_barrier
	v_mfma_f32_16x16x32_bf16 v[126:129], v[130:133], v[180:183], v[126:129]
	v_mfma_f32_16x16x32_bf16 v[122:125], v[138:141], v[180:183], v[122:125]
	v_mfma_f32_16x16x32_bf16 v[110:113], v[130:133], v[188:191], v[110:113]
	v_mfma_f32_16x16x32_bf16 v[106:109], v[138:141], v[188:191], v[106:109]
	v_mfma_f32_16x16x32_bf16 v[94:97], v[130:133], v[200:203], v[94:97]
	v_mfma_f32_16x16x32_bf16 v[90:93], v[138:141], v[200:203], v[90:93]
	v_mfma_f32_16x16x32_bf16 v[78:81], v[130:133], v[222:225], v[78:81]
	v_mfma_f32_16x16x32_bf16 v[74:77], v[138:141], v[222:225], v[74:77]
	v_mfma_f32_16x16x32_bf16 v[126:129], v[134:137], v[184:187], v[126:129]
	v_mfma_f32_16x16x32_bf16 v[122:125], v[142:145], v[184:187], v[122:125]
	v_mfma_f32_16x16x32_bf16 v[110:113], v[134:137], v[196:199], v[110:113]
	v_mfma_f32_16x16x32_bf16 v[106:109], v[142:145], v[196:199], v[106:109]
	v_mfma_f32_16x16x32_bf16 v[94:97], v[134:137], v[216:219], v[94:97]
	v_mfma_f32_16x16x32_bf16 v[90:93], v[142:145], v[216:219], v[90:93]
	v_mfma_f32_16x16x32_bf16 v[78:81], v[134:137], v[226:229], v[78:81]
	v_mfma_f32_16x16x32_bf16 v[74:77], v[142:145], v[226:229], v[74:77]
	v_mfma_f32_16x16x32_bf16 v[118:121], v[158:161], v[180:183], v[118:121]
	v_mfma_f32_16x16x32_bf16 v[114:117], v[166:169], v[180:183], v[114:117]
	v_mfma_f32_16x16x32_bf16 v[102:105], v[158:161], v[188:191], v[102:105]
	v_mfma_f32_16x16x32_bf16 v[98:101], v[166:169], v[188:191], v[98:101]
	v_mfma_f32_16x16x32_bf16 v[86:89], v[158:161], v[200:203], v[86:89]
	v_mfma_f32_16x16x32_bf16 v[82:85], v[166:169], v[200:203], v[82:85]
	v_mfma_f32_16x16x32_bf16 v[70:73], v[158:161], v[222:225], v[70:73]
	v_mfma_f32_16x16x32_bf16 v[66:69], v[166:169], v[222:225], v[66:69]
	v_mfma_f32_16x16x32_bf16 v[118:121], v[162:165], v[184:187], v[118:121]
	v_mfma_f32_16x16x32_bf16 v[114:117], v[170:173], v[184:187], v[114:117]
	v_mfma_f32_16x16x32_bf16 v[102:105], v[162:165], v[196:199], v[102:105]
	v_mfma_f32_16x16x32_bf16 v[98:101], v[170:173], v[196:199], v[98:101]
	v_mfma_f32_16x16x32_bf16 v[86:89], v[162:165], v[216:219], v[86:89]
	v_mfma_f32_16x16x32_bf16 v[82:85], v[170:173], v[216:219], v[82:85]
	v_mfma_f32_16x16x32_bf16 v[70:73], v[162:165], v[226:229], v[70:73]
	v_mfma_f32_16x16x32_bf16 v[66:69], v[170:173], v[226:229], v[66:69]
	s_barrier
	s_setprio 0
	s_add_i32 s14, s93, s51
	v_lshl_add_u64 v[192:193], s[56:57], 0, v[150:151]
	s_mov_b32 m0, s14
	ds_read_b128 v[180:183], v147 offset:16384
	ds_read_b128 v[184:187], v147 offset:17408
	ds_read_b128 v[188:191], v147 offset:18432
	ds_read_b128 v[196:199], v147 offset:19456
	ds_read_b128 v[200:203], v147 offset:20480
	ds_read_b128 v[216:219], v147 offset:21504
	ds_read_b128 v[222:225], v147 offset:22528
	ds_read_b128 v[226:229], v147 offset:23552
	global_load_lds_dwordx4 v[192:193], off
	s_add_i32 m0, s14, 0x2000
	s_add_u32 s14, s56, s50
	v_lshl_add_u64 v[230:231], s[56:57], 0, v[154:155]
	s_addc_u32 s15, s57, 0
	s_add_i32 s6, s6, s51
	global_load_lds_dwordx4 v[230:231], off
	v_lshl_add_u64 v[232:233], s[14:15], 0, v[150:151]
	s_mov_b32 m0, s6
	v_lshl_add_u64 v[234:235], s[14:15], 0, v[154:155]
	global_load_lds_dwordx4 v[232:233], off
	s_add_i32 m0, s6, 0x2000
	v_lshl_add_u64 v[236:237], s[78:79], 0, v[148:149]
	global_load_lds_dwordx4 v[234:235], off
	s_mov_b32 m0, s55
	s_nop 0
	global_load_lds_dwordx4 v[236:237], off
	v_lshl_add_u64 v[236:237], s[78:79], 0, v[152:153]
	s_mov_b32 m0, s58
	s_nop 0
	global_load_lds_dwordx4 v[236:237], off
	s_waitcnt vmcnt(8)
	s_waitcnt lgkmcnt(0)
	s_setprio 1
	s_barrier
; #define S_STAGE(bufoff, gbase, voff) do { _Pragma("unroll") for (int _i = 0; _i < 2; ++_i) \
;     __builtin_amdgcn_global_load_lds((const unsigned*)((gbase) + (voff)[_i]), (LAS unsigned*)(lds + (bufoff) + ldsw + _i * 8192), 16, 0, 0); } while (0)
; #define S_LDA(dst, b, h) do { _Pragma("unroll") for (int m = 0; m < 4; ++m) _Pragma("unroll") for (int k = 0; k < 2; ++k) dst[m][k] = *(const LAS bf16x8*)(lds + S_SA(b, h) + aoff + m * 2048 + k * 1024); } while (0)
; #define S_LDB(dst, b, h) do { _Pragma("unroll") for (int n = 0; n < 2; ++n) _Pragma("unroll") for (int k = 0; k < 2; ++k) dst[n][k] = *(const LAS bf16x8*)(lds + S_SB(b, h) + boff + n * 2048 + k * 1024); } while (0)
; #define S_MMA(ai, bj, At_, Bt_) do { __builtin_amdgcn_s_setprio(1); _Pragma("unroll") for (int m = 0; m < 4; ++m) _Pragma("unroll") for (int n = 0; n < 2; ++n) _Pragma("unroll") for (int k = 0; k < 2; ++k) \
;     acc[ai][bj][m][n] = __builtin_amdgcn_mfma_f32_16x16x32_bf16(Bt_[n][k], At_[m][k], acc[ai][bj][m][n], 0, 0, 0); __builtin_amdgcn_s_setprio(0); } while (0)
; #define S_WAIT_V(n) asm volatile("s_waitcnt vmcnt(" #n ")" ::: "memory")
; #define S_WAIT_L(n) asm volatile("s_waitcnt lgkmcnt(" #n ")" ::: "memory")
; #define S_BAR __builtin_amdgcn_s_barrier()
; #define S_SCHED __builtin_amdgcn_sched_barrier(0)
; DI void gemm_phase(LAS unsigned char* lds, const GemmDesc& d, float* __restrict__ X) {
;     ...
;       S_WAIT_V(8); S_WAIT_L(0); S_BAR; S_MMA(0, 0, At, B0); S_MMA(0, 1, At, B1); S_BAR; S_SCHED;
;       S_LDA(At, 0, 1); S_STAGE(S_SB(0, 0), b2, voffB); S_STAGE(S_SB(0, 1), b2 + hstepB, voffB); S_STAGE(S_SA(0, 0), a2, voffA);
;       S_WAIT_V(8); S_WAIT_L(0); S_BAR; S_MMA(1, 0, At, B0); S_MMA(1, 1, At, B1); S_BAR; S_SCHED;
;       S_LDB(B0, 1, 0); S_LDB(B1, 1, 1); S_SCHED; S_LDA(At, 1, 0); S_STAGE(S_SA(0, 1), a2 + hstepA, voffA);
;       S_WAIT_V(8); S_WAIT_L(0); S_BAR; S_MMA(0, 0, At, B0); S_MMA(0, 1, At, B1); S_BAR; S_SCHED;
	v_mfma_f32_16x16x32_bf16 v[62:65], v[130:133], v[180:183], v[62:65]
	v_mfma_f32_16x16x32_bf16 v[58:61], v[138:141], v[180:183], v[58:61]
	v_mfma_f32_16x16x32_bf16 v[46:49], v[130:133], v[188:191], v[46:49]
	v_mfma_f32_16x16x32_bf16 v[42:45], v[138:141], v[188:191], v[42:45]
	v_mfma_f32_16x16x32_bf16 v[30:33], v[130:133], v[200:203], v[30:33]
	v_mfma_f32_16x16x32_bf16 v[26:29], v[138:141], v[200:203], v[26:29]
	v_mfma_f32_16x16x32_bf16 v[14:17], v[130:133], v[222:225], v[14:17]
	v_mfma_f32_16x16x32_bf16 v[10:13], v[138:141], v[222:225], v[10:13]
	v_mfma_f32_16x16x32_bf16 v[62:65], v[134:137], v[184:187], v[62:65]
	v_mfma_f32_16x16x32_bf16 v[58:61], v[142:145], v[184:187], v[58:61]
	v_mfma_f32_16x16x32_bf16 v[46:49], v[134:137], v[196:199], v[46:49]
	v_mfma_f32_16x16x32_bf16 v[42:45], v[142:145], v[196:199], v[42:45]
	v_mfma_f32_16x16x32_bf16 v[30:33], v[134:137], v[216:219], v[30:33]
	v_mfma_f32_16x16x32_bf16 v[26:29], v[142:145], v[216:219], v[26:29]
	v_mfma_f32_16x16x32_bf16 v[14:17], v[134:137], v[226:229], v[14:17]
	v_mfma_f32_16x16x32_bf16 v[10:13], v[142:145], v[226:229], v[10:13]
	v_mfma_f32_16x16x32_bf16 v[54:57], v[158:161], v[180:183], v[54:57]
	v_mfma_f32_16x16x32_bf16 v[50:53], v[166:169], v[180:183], v[50:53]
	v_mfma_f32_16x16x32_bf16 v[38:41], v[158:161], v[188:191], v[38:41]
	v_mfma_f32_16x16x32_bf16 v[34:37], v[166:169], v[188:191], v[34:37]
	v_mfma_f32_16x16x32_bf16 v[22:25], v[158:161], v[200:203], v[22:25]
	v_mfma_f32_16x16x32_bf16 v[18:21], v[166:169], v[200:203], v[18:21]
	v_mfma_f32_16x16x32_bf16 v[6:9], v[158:161], v[222:225], v[6:9]
	v_mfma_f32_16x16x32_bf16 v[2:5], v[166:169], v[222:225], v[2:5]
	v_mfma_f32_16x16x32_bf16 v[54:57], v[162:165], v[184:187], v[54:57]
	v_mfma_f32_16x16x32_bf16 v[50:53], v[170:173], v[184:187], v[50:53]
	v_mfma_f32_16x16x32_bf16 v[38:41], v[162:165], v[196:199], v[38:41]
	v_mfma_f32_16x16x32_bf16 v[34:37], v[170:173], v[196:199], v[34:37]
	v_mfma_f32_16x16x32_bf16 v[22:25], v[162:165], v[216:219], v[22:25]
	v_mfma_f32_16x16x32_bf16 v[18:21], v[170:173], v[216:219], v[18:21]
	v_mfma_f32_16x16x32_bf16 v[6:9], v[162:165], v[226:229], v[6:9]
	v_mfma_f32_16x16x32_bf16 v[2:5], v[170:173], v[226:229], v[2:5]
	s_barrier
	s_setprio 0
	s_add_i32 s6, 0, 0x18000
	v_add_u32_e32 v0, s6, v174
	s_add_i32 s56, 0, 0x1c000
	ds_read_b128 v[130:133], v0
	ds_read_b128 v[134:137], v0 offset:1024
	ds_read_b128 v[138:141], v0 offset:2048
	ds_read_b128 v[142:145], v0 offset:3072
	v_add_u32_e32 v0, s56, v174
	ds_read_b128 v[158:161], v0
	ds_read_b128 v[162:165], v0 offset:1024
	ds_read_b128 v[166:169], v0 offset:2048
	ds_read_b128 v[170:173], v0 offset:3072
	s_add_u32 s14, s78, s27
	s_addc_u32 s15, s79, 0
	s_mov_b32 m0, s59
	v_lshl_add_u64 v[236:237], s[14:15], 0, v[148:149]
	ds_read_b128 v[180:183], v147 offset:32768
	ds_read_b128 v[184:187], v147 offset:33792
	ds_read_b128 v[188:191], v147 offset:34816
	ds_read_b128 v[196:199], v147 offset:35840
	ds_read_b128 v[200:203], v147 offset:36864
	ds_read_b128 v[216:219], v147 offset:37888
	ds_read_b128 v[222:225], v147 offset:38912
	ds_read_b128 v[226:229], v147 offset:39936
	global_load_lds_dwordx4 v[236:237], off
	v_lshl_add_u64 v[236:237], s[14:15], 0, v[152:153]
	s_mov_b32 m0, s83
	s_nop 0
	global_load_lds_dwordx4 v[236:237], off
	s_waitcnt vmcnt(8)
	s_waitcnt lgkmcnt(0)
	s_setprio 1
	s_barrier
	v_mfma_f32_16x16x32_bf16 v[126:129], v[130:133], v[180:183], v[126:129]
	v_mfma_f32_16x16x32_bf16 v[122:125], v[138:141], v[180:183], v[122:125]
	v_mfma_f32_16x16x32_bf16 v[110:113], v[130:133], v[188:191], v[110:113]
	v_mfma_f32_16x16x32_bf16 v[106:109], v[138:141], v[188:191], v[106:109]
	v_mfma_f32_16x16x32_bf16 v[94:97], v[130:133], v[200:203], v[94:97]
	v_mfma_f32_16x16x32_bf16 v[90:93], v[138:141], v[200:203], v[90:93]
	v_mfma_f32_16x16x32_bf16 v[78:81], v[130:133], v[222:225], v[78:81]
	v_mfma_f32_16x16x32_bf16 v[74:77], v[138:141], v[222:225], v[74:77]
	v_mfma_f32_16x16x32_bf16 v[126:129], v[134:137], v[184:187], v[126:129]
	v_mfma_f32_16x16x32_bf16 v[122:125], v[142:145], v[184:187], v[122:125]
	v_mfma_f32_16x16x32_bf16 v[110:113], v[134:137], v[196:199], v[110:113]
	v_mfma_f32_16x16x32_bf16 v[106:109], v[142:145], v[196:199], v[106:109]
	v_mfma_f32_16x16x32_bf16 v[94:97], v[134:137], v[216:219], v[94:97]
	v_mfma_f32_16x16x32_bf16 v[90:93], v[142:145], v[216:219], v[90:93]
	v_mfma_f32_16x16x32_bf16 v[78:81], v[134:137], v[226:229], v[78:81]
	v_mfma_f32_16x16x32_bf16 v[74:77], v[142:145], v[226:229], v[74:77]
	v_mfma_f32_16x16x32_bf16 v[118:121], v[158:161], v[180:183], v[118:121]
	v_mfma_f32_16x16x32_bf16 v[114:117], v[166:169], v[180:183], v[114:117]
	v_mfma_f32_16x16x32_bf16 v[102:105], v[158:161], v[188:191], v[102:105]
	v_mfma_f32_16x16x32_bf16 v[98:101], v[166:169], v[188:191], v[98:101]
	v_mfma_f32_16x16x32_bf16 v[86:89], v[158:161], v[200:203], v[86:89]
	v_mfma_f32_16x16x32_bf16 v[82:85], v[166:169], v[200:203], v[82:85]
	v_mfma_f32_16x16x32_bf16 v[70:73], v[158:161], v[222:225], v[70:73]
	v_mfma_f32_16x16x32_bf16 v[66:69], v[166:169], v[222:225], v[66:69]
	v_mfma_f32_16x16x32_bf16 v[118:121], v[162:165], v[184:187], v[118:121]
	v_mfma_f32_16x16x32_bf16 v[114:117], v[170:173], v[184:187], v[114:117]
	v_mfma_f32_16x16x32_bf16 v[102:105], v[162:165], v[196:199], v[102:105]
	v_mfma_f32_16x16x32_bf16 v[98:101], v[170:173], v[196:199], v[98:101]
	v_mfma_f32_16x16x32_bf16 v[86:89], v[162:165], v[216:219], v[86:89]
	v_mfma_f32_16x16x32_bf16 v[82:85], v[170:173], v[216:219], v[82:85]
	v_mfma_f32_16x16x32_bf16 v[70:73], v[162:165], v[226:229], v[70:73]
	v_mfma_f32_16x16x32_bf16 v[66:69], v[170:173], v[226:229], v[66:69]
	s_barrier
; #define S_STAGE(bufoff, gbase, voff) do { _Pragma("unroll") for (int _i = 0; _i < 2; ++_i) \
;     __builtin_amdgcn_global_load_lds((const unsigned*)((gbase) + (voff)[_i]), (LAS unsigned*)(lds + (bufoff) + ldsw + _i * 8192), 16, 0, 0); } while (0)
; #define S_LDA(dst, b, h) do { _Pragma("unroll") for (int m = 0; m < 4; ++m) _Pragma("unroll") for (int k = 0; k < 2; ++k) dst[m][k] = *(const LAS bf16x8*)(lds + S_SA(b, h) + aoff + m * 2048 + k * 1024); } while (0)
; #define S_MMA(ai, bj, At_, Bt_) do { __builtin_amdgcn_s_setprio(1); _Pragma("unroll") for (int m = 0; m < 4; ++m) _Pragma("unroll") for (int n = 0; n < 2; ++n) _Pragma("unroll") for (int k = 0; k < 2; ++k) \
;     acc[ai][bj][m][n] = __builtin_amdgcn_mfma_f32_16x16x32_bf16(Bt_[n][k], At_[m][k], acc[ai][bj][m][n], 0, 0, 0); __builtin_amdgcn_s_setprio(0); } while (0)
; #define S_WAIT_V(n) asm volatile("s_waitcnt vmcnt(" #n ")" ::: "memory")
; #define S_WAIT_L(n) asm volatile("s_waitcnt lgkmcnt(" #n ")" ::: "memory")
; #define S_BAR __builtin_amdgcn_s_barrier()
; #define S_SCHED __builtin_amdgcn_sched_barrier(0)
; DI void gemm_phase(LAS unsigned char* lds, const GemmDesc& d, float* __restrict__ X) {
;     ...
;       S_LDA(At, 1, 1); S_STAGE(S_SB(1, 0), b3, voffB); S_STAGE(S_SB(1, 1), b3 + hstepB, voffB); S_STAGE(S_SA(1, 0), a3, voffA);
;       S_WAIT_V(8); S_WAIT_L(0); S_BAR; S_MMA(1, 0, At, B0); S_MMA(1, 1, At, B1); S_BAR; S_SCHED;
;     }
;     if (kwr == 0) S_BAR;
	s_setprio 0
	s_add_i32 s6, s6, s51
	v_lshl_add_u64 v[192:193], v[192:193], 0, s[98:99]
	s_mov_b32 m0, s6
	ds_read_b128 v[180:183], v147 offset:49152
	ds_read_b128 v[184:187], v147 offset:50176
	ds_read_b128 v[188:191], v147 offset:51200
	ds_read_b128 v[196:199], v147 offset:52224
	ds_read_b128 v[200:203], v147 offset:53248
	ds_read_b128 v[216:219], v147 offset:54272
	ds_read_b128 v[222:225], v147 offset:55296
	ds_read_b128 v[226:229], v147 offset:56320
	global_load_lds_dwordx4 v[192:193], off
	v_lshl_add_u64 v[192:193], v[230:231], 0, s[98:99]
	s_add_i32 m0, s6, 0x2000
	s_add_i32 s6, s56, s51
	global_load_lds_dwordx4 v[192:193], off
	v_lshl_add_u64 v[192:193], v[232:233], 0, s[98:99]
	s_mov_b32 m0, s6
	s_nop 0
	global_load_lds_dwordx4 v[192:193], off
	v_lshl_add_u64 v[192:193], v[234:235], 0, s[98:99]
	s_add_i32 m0, s6, 0x2000
	s_nop 0
	global_load_lds_dwordx4 v[192:193], off
	v_lshl_add_u64 v[192:193], s[90:91], 0, v[148:149]
	s_mov_b32 m0, s82
	s_nop 0
	global_load_lds_dwordx4 v[192:193], off
	v_lshl_add_u64 v[192:193], s[90:91], 0, v[152:153]
	s_mov_b32 m0, s94
	s_nop 0
	global_load_lds_dwordx4 v[192:193], off
	s_waitcnt vmcnt(8)
	s_waitcnt lgkmcnt(0)
	s_setprio 1
	s_barrier
	v_mfma_f32_16x16x32_bf16 v[62:65], v[130:133], v[180:183], v[62:65]
	v_mfma_f32_16x16x32_bf16 v[58:61], v[138:141], v[180:183], v[58:61]
	v_mfma_f32_16x16x32_bf16 v[46:49], v[130:133], v[188:191], v[46:49]
	v_mfma_f32_16x16x32_bf16 v[42:45], v[138:141], v[188:191], v[42:45]
	v_mfma_f32_16x16x32_bf16 v[30:33], v[130:133], v[200:203], v[30:33]
	v_mfma_f32_16x16x32_bf16 v[26:29], v[138:141], v[200:203], v[26:29]
	v_mfma_f32_16x16x32_bf16 v[14:17], v[130:133], v[222:225], v[14:17]
	v_mfma_f32_16x16x32_bf16 v[10:13], v[138:141], v[222:225], v[10:13]
	v_mfma_f32_16x16x32_bf16 v[62:65], v[134:137], v[184:187], v[62:65]
	v_mfma_f32_16x16x32_bf16 v[58:61], v[142:145], v[184:187], v[58:61]
	v_mfma_f32_16x16x32_bf16 v[46:49], v[134:137], v[196:199], v[46:49]
	v_mfma_f32_16x16x32_bf16 v[42:45], v[142:145], v[196:199], v[42:45]
	v_mfma_f32_16x16x32_bf16 v[30:33], v[134:137], v[216:219], v[30:33]
	v_mfma_f32_16x16x32_bf16 v[26:29], v[142:145], v[216:219], v[26:29]
	v_mfma_f32_16x16x32_bf16 v[14:17], v[134:137], v[226:229], v[14:17]
	v_mfma_f32_16x16x32_bf16 v[10:13], v[142:145], v[226:229], v[10:13]
	v_mfma_f32_16x16x32_bf16 v[54:57], v[158:161], v[180:183], v[54:57]
	v_mfma_f32_16x16x32_bf16 v[50:53], v[166:169], v[180:183], v[50:53]
	v_mfma_f32_16x16x32_bf16 v[38:41], v[158:161], v[188:191], v[38:41]
	v_mfma_f32_16x16x32_bf16 v[34:37], v[166:169], v[188:191], v[34:37]
	v_mfma_f32_16x16x32_bf16 v[22:25], v[158:161], v[200:203], v[22:25]
	v_mfma_f32_16x16x32_bf16 v[18:21], v[166:169], v[200:203], v[18:21]
	v_mfma_f32_16x16x32_bf16 v[6:9], v[158:161], v[222:225], v[6:9]
	v_mfma_f32_16x16x32_bf16 v[2:5], v[166:169], v[222:225], v[2:5]
	v_mfma_f32_16x16x32_bf16 v[54:57], v[162:165], v[184:187], v[54:57]
	v_mfma_f32_16x16x32_bf16 v[50:53], v[170:173], v[184:187], v[50:53]
	v_mfma_f32_16x16x32_bf16 v[38:41], v[162:165], v[196:199], v[38:41]
	v_mfma_f32_16x16x32_bf16 v[34:37], v[170:173], v[196:199], v[34:37]
	v_mfma_f32_16x16x32_bf16 v[22:25], v[162:165], v[216:219], v[22:25]
	v_mfma_f32_16x16x32_bf16 v[18:21], v[170:173], v[216:219], v[18:21]
	v_mfma_f32_16x16x32_bf16 v[6:9], v[162:165], v[226:229], v[6:9]
	v_mfma_f32_16x16x32_bf16 v[2:5], v[170:173], v[226:229], v[2:5]
	s_barrier
	s_setprio 0
	s_add_u32 s64, s64, 0x100
	s_addc_u32 s69, s69, 0
	s_cmp_ge_u32 vcc_lo, s1
	s_mov_b64 s[90:91], vcc
	s_cbranch_scc0 .LBB0_346
	s_and_b64 vcc, exec, s[74:75]
	s_cbranch_vccz .LBB0_349
	s_barrier
